# baseline (speedup 1.0000x reference)
; template <bool FOX, int G>
; __device__ __forceinline__ void p3_attn(const Ptrs<G>& w, int seq, int h, int qb, bfu* sm, int kslot) {
;     ...
;     {
;       const bool wd = (__builtin_amdgcn_ballot_w64(done) == ~0ull);
;       if (lane == 0) vote[wave] = wd ? 1 : 0;
;       __syncthreads();
;       if ((vote[0] & vote[1] & vote[2] & vote[3]) != 0) break;
;     }
; #pragma unroll
;     for (int q = 0; q < 2; ++q) {
;       *(bf16x8*)(Ks + (lrow + 32 * q) * 72 + lch) = rk[q];
;       *(bf16x8*)(Vs + (lrow + 32 * q) * 72 + lch) = rv[q];
;     }
;     __syncthreads();
;     if (kt > 0) {
;       const int s1 = (kt - 1) * 64;
; #pragma unroll
;       for (int q = 0; q < 2; ++q) {
;         rk[q] = *(const bf16x8*)(qk + (rowbase + s1 + lrow + 32 * q) * 1024 + 512 + h * 64 + lch);
;         rv[q] = *(const bf16x8*)(Vt + (size_t)(lrow + 32 * q) * TSEQ + s1 + lch);
;       }
;     }
.LBB0_323:
	s_or_b64 exec, exec, s[0:1]
	s_mov_b64 s[0:1], src_shared_base
	v_mov_b32_e32 v157, s1
	v_mov_b32_e32 v159, s1
	s_waitcnt lgkmcnt(0)
	s_barrier
	ds_read_b128 v[64:67], v156
	v_mov_b32_e32 v161, s1
	v_mov_b32_e32 v163, s1
	s_mov_b64 s[0:1], -1
	s_waitcnt vmcnt(0) lgkmcnt(0)
	v_and_b32_e32 v64, v65, v64
	v_bitop3_b32 v64, v64, v67, v66 bitop3:0x80
	v_cmp_eq_u32_e32 vcc, 0, v64
	s_and_saveexec_b64 s[18:19], vcc
	s_cbranch_execz .LBB0_320
	s_cmp_eq_u32 s28, 1
	ds_write_b128 v138, v[36:39]
	ds_write_b128 v138, v[40:43] offset:9216
	ds_write_b128 v138, v[44:47] offset:4608
	ds_write_b128 v138, v[32:35] offset:13824
	s_waitcnt lgkmcnt(0)
	s_barrier
	s_cbranch_scc1 .LBB0_326
	s_mov_b32 s13, s3
	v_lshl_add_u64 v[32:33], v[134:135], 0, s[12:13]
	v_lshlrev_b64 v[32:33], 11, v[32:33]
	v_lshl_add_u64 v[32:33], s[64:65], 0, v[32:33]
	s_lshl_b32 s0, s27, 1
	s_mov_b32 s1, s3
	v_lshl_add_u64 v[34:35], s[12:13], 1, v[136:137]
	v_lshl_add_u64 v[32:33], v[32:33], 0, s[0:1]
	v_lshl_add_u64 v[32:33], v[32:33], 0, v[152:153]
	v_lshl_add_u64 v[40:41], v[34:35], 0, v[124:125]
	global_load_dwordx4 v[36:39], v[32:33], off offset:1024
	s_nop 0
	global_load_dwordx4 v[40:43], v[40:41], off
	v_add_co_u32_e32 v32, vcc, 0x10000, v32
	v_lshl_add_u64 v[34:35], v[34:35], 0, v[126:127]
	s_nop 0
	v_addc_co_u32_e32 v33, vcc, 0, v33, vcc
	global_load_dwordx4 v[44:47], v[32:33], off offset:1024
	s_nop 0
	global_load_dwordx4 v[32:35], v[34:35], off

; template <bool FOX, int G>
; __device__ __forceinline__ void p3_attn(const Ptrs<G>& w, int seq, int h, int qb, bfu* sm, int kslot) {
;     ...
;     {
;       const bool wd = (__builtin_amdgcn_ballot_w64(done) == ~0ull);
;       if (lane == 0) vote[wave] = wd ? 1 : 0;
;       __syncthreads();
;       if ((vote[0] & vote[1] & vote[2] & vote[3]) != 0) break;
;     }
; #pragma unroll
;     for (int q = 0; q < 2; ++q) {
;       *(bf16x8*)(Ks + (lrow + 32 * q) * 72 + lch) = rk[q];
;       *(bf16x8*)(Vs + (lrow + 32 * q) * 72 + lch) = rv[q];
;     }
;     __syncthreads();
;     if (kt > 0) {
;       const int s1 = (kt - 1) * 64;
; #pragma unroll
;       for (int q = 0; q < 2; ++q) {
;         rk[q] = *(const bf16x8*)(qk + (rowbase + s1 + lrow + 32 * q) * 1024 + 512 + h * 64 + lch);
;         rv[q] = *(const bf16x8*)(Vt + (size_t)(lrow + 32 * q) * TSEQ + s1 + lch);
;       }
;     }
.LBB0_336:
	s_or_b64 exec, exec, s[0:1]
	s_mov_b64 s[0:1], src_shared_base
	v_mov_b32_e32 v157, s1
	v_mov_b32_e32 v159, s1
	s_waitcnt lgkmcnt(0)
	s_barrier
	ds_read_b128 v[64:67], v156
	v_mov_b32_e32 v161, s1
	v_mov_b32_e32 v163, s1
	s_mov_b64 s[0:1], -1
	s_waitcnt vmcnt(0) lgkmcnt(0)
	v_and_b32_e32 v64, v65, v64
	v_bitop3_b32 v64, v64, v67, v66 bitop3:0x80
	v_cmp_eq_u32_e32 vcc, 0, v64
	s_and_saveexec_b64 s[92:93], vcc
	s_cbranch_execz .LBB0_333
	s_cmp_eq_u32 s73, 1
	ds_write_b128 v112, v[48:51]
	ds_write_b128 v112, v[28:31] offset:9216
	ds_write_b128 v112, v[56:59] offset:4608
	ds_write_b128 v112, v[40:43] offset:13824
	s_waitcnt lgkmcnt(0)
	s_barrier
	s_cbranch_scc1 .LBB0_339
	s_sub_i32 s2, s72, 64
	v_lshl_add_u64 v[28:29], v[108:109], 0, s[2:3]
	v_readlane_b32 s0, v254, 12
	v_lshlrev_b64 v[28:29], 11, v[28:29]
	v_readlane_b32 s1, v254, 13
	v_lshl_add_u64 v[40:41], s[2:3], 1, v[110:111]
	s_lshl_b32 s2, s87, 1
	v_lshl_add_u64 v[28:29], s[0:1], 0, v[28:29]
	v_lshl_add_u64 v[28:29], v[28:29], 0, s[2:3]
	v_lshl_add_u64 v[42:43], v[28:29], 0, v[152:153]
	v_lshl_add_u64 v[28:29], v[40:41], 0, v[102:103]
	s_mov_b32 s0, 0x10000
	global_load_dwordx4 v[48:51], v[42:43], off offset:1024
	s_nop 0
	global_load_dwordx4 v[28:31], v[28:29], off
	v_add_co_u32_e32 v42, vcc, s0, v42
	v_lshl_add_u64 v[40:41], v[40:41], 0, v[104:105]
	s_nop 0
	v_addc_co_u32_e32 v43, vcc, 0, v43, vcc
	global_load_dwordx4 v[56:59], v[42:43], off offset:1024
	s_nop 0
	global_load_dwordx4 v[40:43], v[40:41], off
	s_mov_b32 s0, s72
	v_cmp_le_i32_e32 vcc, s0, v98
	s_and_saveexec_b64 s[94:95], vcc
	s_cbranch_execz .LBB0_332
	s_branch .LBB0_340
